# also seam 7: fix_gate pass runs only on the 128 WGs without a K-split piece in the w_o GEMM and signals a counter; piece owners poll it late in their full unit's K-loop
# baseline (speedup 1.0000x reference)
; __device__ __forceinline__ float bf_lo(unsigned w) { return __uint_as_float(w << 16); }
; __device__ __forceinline__ float bf_hi(unsigned w) { return __uint_as_float(w & 0xffff0000u); }
; __device__ __forceinline__ void fix_gate(const float* part, int nsl, const bf16_t* z, bf16_t* mixed, int gw, int ngw, int lane) {
;     for (int it = gw; it < NTAIL * 8; it += ngw) {
;         const int rloc = it >> 3, row = TAIL0 + rloc, col = (it & 7) * 256 + lane * 4;
;         const bf16_t* p = (const bf16_t*)part + (size_t)rloc * 2048 + col;
;         f32x4_t a = (f32x4_t){0.f, 0.f, 0.f, 0.f}, b = (f32x4_t){0.f, 0.f, 0.f, 0.f};
; #pragma unroll 8
;         for (int s = 0; s < nsl; ++s) { const u32x2_t wa = __builtin_nontemporal_load((const u32x2_t*)(p + (size_t)s * (256 * 2048))), wb = __builtin_nontemporal_load((const u32x2_t*)(p + (size_t)(s + nsl) * (256 * 2048)));
;             a += (f32x4_t){bf_lo(wa.x), bf_hi(wa.x), bf_lo(wa.y), bf_hi(wa.y)}; b += (f32x4_t){bf_lo(wb.x), bf_hi(wb.x), bf_lo(wb.y), bf_hi(wb.y)}; }
;         const u32x2_t gc = *(const u32x2_t*)(z + (size_t)row * DIN + ZO_GC + col), ga = *(const u32x2_t*)(z + (size_t)row * DIN + ZO_GA + col);
.LBB0_1038:
	s_cmp_lt_i32 s66, 8
	s_cselect_b64 s[6:7], -1, 0
	s_and_b64 s[6:7], s[6:7], s[0:1]
	s_cmpk_gt_u32 s33, 127
	s_cselect_b64 s[0:1], -1, 0
	s_and_b64 s[0:1], s[6:7], s[0:1]
	s_andn2_b64 vcc, exec, s[0:1]
	s_cbranch_vccnz .LBB0_1041
	v_readlane_b32 s1, v251, 29
	s_sub_i32 s0, s33, 128
	s_lshl_b32 s0, s0, 11
	s_lshl_b32 s1, s1, 8
	s_add_i32 s2, s0, s1
	s_mov_b32 s10, 0x40000
	s_waitcnt lgkmcnt(0)
	v_mov_b32_e32 v1, 0
	s_mov_b32 s12, 0x800000
	s_mov_b32 s13, 0x100000
	s_mov_b32 s14, 0x900000
	s_mov_b32 s15, 0x200000
	s_mov_b32 s20, 0xa00000
	s_mov_b32 s21, 0x300000
	s_mov_b32 s22, 0xb00000
	s_mov_b32 s23, 0x400000
	s_mov_b32 s24, 0xc00000
	s_mov_b32 s25, 0x500000
	s_mov_b32 s26, 0xd00000
	s_mov_b32 s27, 0x600000
	s_mov_b32 s28, 0xe00000
	s_mov_b32 s29, 0x700000
	s_mov_b32 s30, 0xf00000
	s_movk_i32 s31, 0x2000
	s_movk_i32 s34, 0x3000
	s_lshr_b32 s35, s2, 8
.LBB0_1040:
	s_ashr_i32 s0, s35, 3
	s_and_b32 s1, s2, 0x700
	v_or_b32_e32 v0, s1, v241
	s_ashr_i32 s1, s0, 31
	s_lshl_b64 s[16:17], s[0:1], 12
	s_add_u32 s16, s86, s16
	v_lshlrev_b32_e32 v0, 1, v0
	s_addc_u32 s17, s87, s17
	v_lshl_add_u64 v[2:3], s[16:17], 0, v[0:1]
	s_add_i32 s18, s0, 0x2000
	v_add_co_u32_e64 v8, s[0:1], s13, v2
	global_load_dwordx2 v[4:5], v0, s[16:17] nt
	s_nop 0
	v_addc_co_u32_e64 v9, s[0:1], 0, v3, s[0:1]
	v_add_co_u32_e64 v10, s[0:1], s14, v2
	v_add_co_u32_e32 v6, vcc, s12, v2
	s_nop 0
	v_addc_co_u32_e64 v11, s[0:1], 0, v3, s[0:1]
	v_add_co_u32_e64 v12, s[0:1], s15, v2
	s_ashr_i32 s19, s18, 31
	s_nop 0
	v_addc_co_u32_e64 v13, s[0:1], 0, v3, s[0:1]
	v_add_co_u32_e64 v14, s[0:1], s20, v2
	s_mul_i32 s17, s18, 0x4400
	s_nop 0
	v_addc_co_u32_e64 v15, s[0:1], 0, v3, s[0:1]
	v_add_co_u32_e64 v16, s[0:1], s21, v2
	v_addc_co_u32_e32 v7, vcc, 0, v3, vcc
	s_nop 0
	v_addc_co_u32_e64 v17, s[0:1], 0, v3, s[0:1]
	v_add_co_u32_e64 v18, s[0:1], s22, v2
	s_mul_hi_i32 s16, s18, 0x4400
	s_nop 0
	v_addc_co_u32_e64 v19, s[0:1], 0, v3, s[0:1]
	v_add_co_u32_e64 v20, s[0:1], s23, v2
	s_waitcnt vmcnt(0)
	v_lshlrev_b32_e32 v38, 16, v4
	v_addc_co_u32_e64 v21, s[0:1], 0, v3, s[0:1]
	v_add_co_u32_e64 v22, s[0:1], s24, v2
	v_and_b32_e32 v39, 0xffff0000, v4
	s_nop 0
	v_addc_co_u32_e64 v23, s[0:1], 0, v3, s[0:1]
	v_add_co_u32_e64 v24, s[0:1], s25, v2
	v_lshlrev_b32_e32 v4, 16, v5
	s_nop 0
	v_addc_co_u32_e64 v25, s[0:1], 0, v3, s[0:1]
	v_add_co_u32_e64 v26, s[0:1], s26, v2
	v_and_b32_e32 v5, 0xffff0000, v5
	s_nop 0
	v_addc_co_u32_e64 v27, s[0:1], 0, v3, s[0:1]
	v_add_co_u32_e64 v28, s[0:1], s27, v2
	v_pk_add_f32 v[38:39], v[38:39], 0 op_sel_hi:[1,0]
	s_nop 0
	v_addc_co_u32_e64 v29, s[0:1], 0, v3, s[0:1]
	v_add_co_u32_e64 v30, s[0:1], s28, v2
	v_pk_add_f32 v[4:5], v[4:5], 0 op_sel_hi:[1,0]
	s_nop 0
	v_addc_co_u32_e64 v31, s[0:1], 0, v3, s[0:1]
	v_add_co_u32_e64 v32, s[0:1], s29, v2
	s_nop 1
	v_addc_co_u32_e64 v33, s[0:1], 0, v3, s[0:1]
	v_add_co_u32_e64 v34, s[0:1], s30, v2
	s_nop 1
	v_addc_co_u32_e64 v35, s[0:1], 0, v3, s[0:1]
	s_add_u32 s0, s4, s17
	global_load_dwordx2 v[14:15], v[14:15], off nt
	s_nop 0
	global_load_dwordx2 v[16:17], v[16:17], off nt
	s_nop 0
	global_load_dwordx2 v[18:19], v[18:19], off nt
	s_nop 0
	global_load_dwordx2 v[20:21], v[20:21], off nt
	s_nop 0
	global_load_dwordx2 v[22:23], v[22:23], off nt
	s_nop 0
	global_load_dwordx2 v[24:25], v[24:25], off nt
	s_nop 0
	global_load_dwordx2 v[26:27], v[26:27], off nt
	s_nop 0
	global_load_dwordx2 v[28:29], v[28:29], off nt
	s_nop 0
	global_load_dwordx2 v[30:31], v[30:31], off nt
	s_nop 0
	global_load_dwordx2 v[32:33], v[32:33], off nt
	s_nop 0
	global_load_dwordx2 v[34:35], v[34:35], off nt
	s_nop 0
	global_load_dwordx2 v[2:3], v[6:7], off nt
	s_nop 0
	global_load_dwordx2 v[6:7], v[8:9], off nt
	s_nop 0
	global_load_dwordx2 v[8:9], v[10:11], off nt
	s_nop 0
	global_load_dwordx2 v[10:11], v[12:13], off nt
	s_addc_u32 s1, s5, s16
	v_lshl_add_u64 v[12:13], s[0:1], 0, v[0:1]
	v_add_co_u32_e32 v36, vcc, s31, v12
	s_lshl_b64 s[16:17], s[18:19], 12
	s_nop 0
	v_addc_co_u32_e32 v37, vcc, 0, v13, vcc
	v_add_co_u32_e32 v12, vcc, s34, v12
	s_add_u32 s0, s8, s16
	s_nop 0
	v_addc_co_u32_e32 v13, vcc, 0, v13, vcc
	global_load_dwordx2 v[12:13], v[12:13], off offset:1024
	s_nop 0
	global_load_dwordx2 v[36:37], v[36:37], off offset:1024
	s_addc_u32 s1, s9, s17
	s_addk_i32 s35, 0x400
	s_add_i32 s2, s2, s10
	s_cmpk_lt_i32 s35, 0x600
	s_waitcnt vmcnt(16)
	v_lshlrev_b32_e32 v40, 16, v14
	v_and_b32_e32 v41, 0xffff0000, v14
	v_lshlrev_b32_e32 v14, 16, v15
	v_and_b32_e32 v15, 0xffff0000, v15
	s_waitcnt vmcnt(15)
	v_lshlrev_b32_e32 v42, 16, v16
	v_and_b32_e32 v43, 0xffff0000, v16
	v_lshlrev_b32_e32 v16, 16, v17
	v_and_b32_e32 v17, 0xffff0000, v17
	s_waitcnt vmcnt(5)
	v_lshlrev_b32_e32 v62, 16, v2
	v_and_b32_e32 v63, 0xffff0000, v2
	v_lshlrev_b32_e32 v2, 16, v3
	v_and_b32_e32 v3, 0xffff0000, v3
	s_waitcnt vmcnt(4)
	v_lshlrev_b32_e32 v64, 16, v6
	v_and_b32_e32 v65, 0xffff0000, v6
	v_lshlrev_b32_e32 v6, 16, v7
	v_and_b32_e32 v7, 0xffff0000, v7
	s_waitcnt vmcnt(3)
; __device__ __forceinline__ float bf_lo(unsigned w) { return __uint_as_float(w << 16); }
; __device__ __forceinline__ float bf_hi(unsigned w) { return __uint_as_float(w & 0xffff0000u); }
; __device__ __forceinline__ unsigned pk2(float lo, float hi) { return pg8::cvt_pk_bf16(lo, hi); }
; #define SEAM(k) do { if (IN(k) && IN((k) + 1)) { if (FLAT_BARRIER) flat_barrier((unsigned*)(ws + WS_BAR) + 64); else xcd_barrier(bar); } } while (0)
; __device__ __forceinline__ void fix_gate(const float* part, int nsl, const bf16_t* z, bf16_t* mixed, int gw, int ngw, int lane) {
;     ...
;         for (int s = 0; s < nsl; ++s) { const u32x2_t wa = __builtin_nontemporal_load((const u32x2_t*)(p + (size_t)s * (256 * 2048))), wb = __builtin_nontemporal_load((const u32x2_t*)(p + (size_t)(s + nsl) * (256 * 2048)));
;             a += (f32x4_t){bf_lo(wa.x), bf_hi(wa.x), bf_lo(wa.y), bf_hi(wa.y)}; b += (f32x4_t){bf_lo(wb.x), bf_hi(wb.x), bf_lo(wb.y), bf_hi(wb.y)}; }
;         const u32x2_t gc = *(const u32x2_t*)(z + (size_t)row * DIN + ZO_GC + col), ga = *(const u32x2_t*)(z + (size_t)row * DIN + ZO_GA + col);
;         u32x2_t w;
;         w.x = pk2(bf_lo(gc.x) * a.x + bf_lo(ga.x) * b.x, bf_hi(gc.x) * a.y + bf_hi(ga.x) * b.y);
;         w.y = pk2(bf_lo(gc.y) * a.z + bf_lo(ga.y) * b.z, bf_hi(gc.y) * a.w + bf_hi(ga.y) * b.w);
;         *(u32x2_t*)(mixed + (size_t)row * DM + col) = w;
;     }
; __global__ void __launch_bounds__(NWAVES * 64, 2) fwd_megakernel(Args args) {
;     ...
;     SEAM(7);
	v_lshlrev_b32_e32 v66, 16, v8
	v_and_b32_e32 v67, 0xffff0000, v8
	v_lshlrev_b32_e32 v8, 16, v9
	v_and_b32_e32 v9, 0xffff0000, v9
	v_pk_add_f32 v[62:63], v[62:63], 0 op_sel_hi:[1,0]
	v_pk_add_f32 v[2:3], v[2:3], 0 op_sel_hi:[1,0]
	s_waitcnt vmcnt(2)
	v_lshlrev_b32_e32 v68, 16, v10
	v_and_b32_e32 v69, 0xffff0000, v10
	v_lshlrev_b32_e32 v10, 16, v11
	v_and_b32_e32 v11, 0xffff0000, v11
	v_pk_add_f32 v[4:5], v[4:5], v[6:7]
	v_pk_add_f32 v[6:7], v[38:39], v[64:65]
	v_pk_add_f32 v[2:3], v[2:3], v[8:9]
	v_pk_add_f32 v[8:9], v[62:63], v[66:67]
	v_lshlrev_b32_e32 v44, 16, v18
	v_and_b32_e32 v45, 0xffff0000, v18
	v_lshlrev_b32_e32 v18, 16, v19
	v_and_b32_e32 v19, 0xffff0000, v19
	v_pk_add_f32 v[6:7], v[6:7], v[68:69]
	v_pk_add_f32 v[4:5], v[4:5], v[10:11]
	v_pk_add_f32 v[8:9], v[8:9], v[40:41]
	v_pk_add_f32 v[2:3], v[2:3], v[14:15]
	v_lshlrev_b32_e32 v46, 16, v20
	v_and_b32_e32 v47, 0xffff0000, v20
	v_lshlrev_b32_e32 v20, 16, v21
	v_and_b32_e32 v21, 0xffff0000, v21
	v_lshlrev_b32_e32 v48, 16, v22
	v_and_b32_e32 v49, 0xffff0000, v22
	v_lshlrev_b32_e32 v22, 16, v23
	v_and_b32_e32 v23, 0xffff0000, v23
	v_pk_add_f32 v[4:5], v[4:5], v[16:17]
	v_pk_add_f32 v[6:7], v[6:7], v[42:43]
	v_pk_add_f32 v[2:3], v[2:3], v[18:19]
	v_pk_add_f32 v[8:9], v[8:9], v[44:45]
	v_lshlrev_b32_e32 v50, 16, v24
	v_and_b32_e32 v51, 0xffff0000, v24
	v_lshlrev_b32_e32 v24, 16, v25
	v_and_b32_e32 v25, 0xffff0000, v25
	v_lshlrev_b32_e32 v52, 16, v26
	v_and_b32_e32 v53, 0xffff0000, v26
	v_lshlrev_b32_e32 v26, 16, v27
	v_and_b32_e32 v27, 0xffff0000, v27
	v_pk_add_f32 v[6:7], v[6:7], v[46:47]
	v_pk_add_f32 v[4:5], v[4:5], v[20:21]
	v_pk_add_f32 v[8:9], v[8:9], v[48:49]
	v_pk_add_f32 v[2:3], v[2:3], v[22:23]
	v_lshlrev_b32_e32 v54, 16, v28
	v_and_b32_e32 v55, 0xffff0000, v28
	v_lshlrev_b32_e32 v28, 16, v29
	v_and_b32_e32 v29, 0xffff0000, v29
	v_lshlrev_b32_e32 v56, 16, v30
	v_and_b32_e32 v57, 0xffff0000, v30
	v_lshlrev_b32_e32 v30, 16, v31
	v_and_b32_e32 v31, 0xffff0000, v31
	v_pk_add_f32 v[4:5], v[4:5], v[24:25]
	v_pk_add_f32 v[6:7], v[6:7], v[50:51]
	v_pk_add_f32 v[2:3], v[2:3], v[26:27]
	v_pk_add_f32 v[8:9], v[8:9], v[52:53]
	v_lshlrev_b32_e32 v58, 16, v32
	v_and_b32_e32 v59, 0xffff0000, v32
	v_lshlrev_b32_e32 v32, 16, v33
	v_and_b32_e32 v33, 0xffff0000, v33
	v_lshlrev_b32_e32 v60, 16, v34
	v_and_b32_e32 v61, 0xffff0000, v34
	v_lshlrev_b32_e32 v34, 16, v35
	v_and_b32_e32 v35, 0xffff0000, v35
	v_pk_add_f32 v[6:7], v[6:7], v[54:55]
	v_pk_add_f32 v[4:5], v[4:5], v[28:29]
	v_pk_add_f32 v[8:9], v[8:9], v[56:57]
	v_pk_add_f32 v[2:3], v[2:3], v[30:31]
	v_pk_add_f32 v[4:5], v[4:5], v[32:33]
	v_pk_add_f32 v[6:7], v[6:7], v[58:59]
	v_pk_add_f32 v[2:3], v[2:3], v[34:35]
	v_pk_add_f32 v[8:9], v[8:9], v[60:61]
	s_waitcnt vmcnt(1)
	v_lshlrev_b32_e32 v11, 16, v12
	v_and_b32_e32 v39, 0xffff0000, v12
	v_lshlrev_b32_e32 v63, 16, v13
	v_and_b32_e32 v13, 0xffff0000, v13
	s_waitcnt vmcnt(0)
	v_and_b32_e32 v12, 0xffff0000, v37
	v_mov_b32_e32 v15, v8
	v_mov_b32_e32 v8, v7
	v_mov_b32_e32 v7, v2
	v_mov_b32_e32 v2, v5
	v_lshlrev_b32_e32 v10, 16, v36
	v_and_b32_e32 v38, 0xffff0000, v36
	v_lshlrev_b32_e32 v62, 16, v37
	v_mov_b32_e32 v14, v6
	v_mov_b32_e32 v6, v4
	v_pk_mul_f32 v[2:3], v[2:3], v[12:13]
	v_pk_mul_f32 v[4:5], v[14:15], v[10:11]
	v_pk_mul_f32 v[8:9], v[8:9], v[38:39]
	v_pk_mul_f32 v[6:7], v[6:7], v[62:63]
	v_add_f32_e32 v3, v2, v3
	v_add_f32_e32 v4, v4, v5
	v_add_f32_e32 v5, v8, v9
	v_add_f32_e32 v6, v6, v7
	v_cvt_pk_bf16_f32 v2, v4, v5
	v_cvt_pk_bf16_f32 v3, v6, v3
	global_store_dwordx2 v0, v[2:3], s[0:1] sc0 sc1
	s_cbranch_scc1 .LBB0_1040
.LBB0_1041:
	s_cmp_gt_i32 s67, 8
	s_cselect_b64 s[0:1], -1, 0
	s_and_b64 s[6:7], s[6:7], s[0:1]
	s_andn2_b64 vcc, exec, s[6:7]
	s_cbranch_vccnz .LBB0_1095
	s_cmpk_lt_u32 s33, 128
	s_cbranch_scc1 .LBB0_1095
	s_waitcnt vmcnt(0) lgkmcnt(0)
	s_barrier
	s_mov_b64 s[98:99], exec
	v_readlane_b32 s100, v251, 27
	v_readlane_b32 s101, v251, 28
	s_and_b64 s[100:101], s[98:99], s[100:101]
	s_mov_b64 exec, s[100:101]
	s_cbranch_execz .Lsig7_done
	s_add_u32 s100, s90, 0x3800
	s_addc_u32 s101, s91, 0
	v_mov_b32_e32 v16, 0
	v_mov_b32_e32 v0, 1
	global_atomic_add v16, v0, s[100:101]
.Lsig7_done:
	s_mov_b64 exec, s[98:99]
	s_branch .LBB0_1095
	s_waitcnt vmcnt(0)
	s_waitcnt vmcnt(0) lgkmcnt(0)
	s_barrier
	s_mov_b64 s[6:7], exec
	v_readlane_b32 s12, v251, 27
	v_readlane_b32 s13, v251, 28
	s_and_b64 s[12:13], s[6:7], s[12:13]
	s_mov_b64 exec, s[12:13]
	s_cbranch_execz .LBB0_1094
	s_add_i32 s2, 0, 0x21000
	v_mov_b32_e32 v0, s2
	s_waitcnt vmcnt(0) expcnt(0) lgkmcnt(0)
	ds_read_b32 v2, v0
	s_add_i32 s2, 0, 0x21004
	v_mov_b32_e32 v0, s2
	ds_read_b32 v0, v0
	s_waitcnt lgkmcnt(1)
	v_cmp_ne_u32_e32 vcc, 0, v2
	s_cbranch_vccnz .LBB0_1058
	v_readlane_b32 s14, v251, 0
	v_readlane_b32 s15, v251, 1
	s_add_u32 s16, s90, 0x1000
	s_load_dwordx2 s[12:13], s[14:15], 0x4
	s_addc_u32 s17, s91, 0
	s_add_u32 s18, s90, 0x1100
	s_addc_u32 s19, s91, 0
	s_add_u32 s20, s90, 0x1200
	s_addc_u32 s21, s91, 0
	s_waitcnt lgkmcnt(0)
	s_mul_i32 s2, s12, s3
	s_add_u32 s22, s90, 0x1300
	s_mul_i32 s2, s2, s13
	s_addc_u32 s23, s91, 0
	s_mov_b32 s10, 1
	v_mov_b32_e32 v16, 0
	s_branch .LBB0_1046

; template <class Epi, class Sched, bool ALIGN_EPI = false, bool SP2 = false>
; __device__ __forceinline__ void gemm_phase(PG8_LAS unsigned char* lds, const Gemm g, const Sched& S, const Epi& E) {
;     ...
;     for (;;) {
;         const bool has_next = S.next(ui + 1, nxt);
;         const char* nA = has_next ? (const char*)g.A + (size_t)nxt.pm * tstep + (size_t)nxt.k0 * kstepA : cA; const char* nB = has_next ? (const char*)g.Bt + (size_t)nxt.pn * tstep + (size_t)nxt.k0 * kstepB : cB;
.LBB0_1112:
	s_mov_b32 s32, 0
	s_cmp_lg_u32 s28, 32
	s_cbranch_scc1 .Lhf8
	s_mov_b32 s32, 1

; #define PG8_STAGE(bufoff, gbase, voff) do { _Pragma("unroll") for (int _i = 0; _i < 2; ++_i) \
;         __builtin_amdgcn_global_load_lds((const unsigned*)((const char*)(gbase) + (voff)[_i]), (PG8_LAS unsigned*)(lds + (bufoff) + ldsw + _i * 8192), 16, 0, 0); } while (0)
; #define PG8_LDA(dst, b, h) do { _Pragma("unroll") for (int m = 0; m < 4; ++m) _Pragma("unroll") for (int k = 0; k < 2; ++k) dst[m][k] = *(const PG8_LAS bf16x8*)(lds + PG8_SA(b, h) + aoff + m * 2048 + k * 1024); } while (0)
; #define PG8_LDB(dst, b, h) do { _Pragma("unroll") for (int n = 0; n < 2; ++n) _Pragma("unroll") for (int k = 0; k < 2; ++k) dst[n][k] = *(const PG8_LAS bf16x8*)(lds + PG8_SB(b, h) + boff + n * 2048 + k * 1024); } while (0)
; #define PG8_MMA(ai, bj, At, Bt) do { __builtin_amdgcn_s_setprio(1); _Pragma("unroll") for (int m = 0; m < 4; ++m) _Pragma("unroll") for (int n = 0; n < 2; ++n) _Pragma("unroll") for (int k = 0; k < 2; ++k) \
;         acc[ai][bj][m][n] = __builtin_amdgcn_mfma_f32_16x16x32_bf16(Bt[n][k], At[m][k], acc[ai][bj][m][n], 0, 0, 0); __builtin_amdgcn_s_setprio(0); } while (0)
; #define PG8_WAIT_V(n) asm volatile("s_waitcnt vmcnt(" #n ")" ::: "memory")
; #define PG8_WAIT_L(n) asm volatile("s_waitcnt lgkmcnt(" #n ")" ::: "memory")
; #define PG8_BAR __builtin_amdgcn_s_barrier()
; #define PG8_SCHED __builtin_amdgcn_sched_barrier(0)
; template <class Epi, class Sched, bool ALIGN_EPI = false, bool SP2 = false>
; __device__ __forceinline__ void gemm_phase(PG8_LAS unsigned char* lds, const Gemm g, const Sched& S, const Epi& E) {
;     ...
;             PG8_LDB(B0, 0, 0); PG8_LDB(B1, 0, 1); PG8_SCHED; PG8_LDA(At, 0, 0); PG8_STAGE(PG8_SA(1, 1), a1 + hstepA, voffA);
;             PG8_WAIT_V(8); PG8_WAIT_L(0); PG8_BAR; PG8_MMA(0, 0, At, B0); PG8_MMA(0, 1, At, B1); PG8_BAR; PG8_SCHED;
;             PG8_LDA(At, 0, 1); PG8_STAGE(PG8_SB(0, 0), b2, voffB); PG8_STAGE(PG8_SB(0, 1), b2 + hstepB, voffB); PG8_STAGE(PG8_SA(0, 0), a2, voffA);
;             PG8_WAIT_V(8); PG8_WAIT_L(0); PG8_BAR; PG8_MMA(1, 0, At, B0); PG8_MMA(1, 1, At, B1); PG8_BAR; PG8_SCHED;
.LBB0_1113:
	s_sub_u32 s100, s42, 0x80000
	s_subb_u32 s101, s43, 0
	ds_read_b128 v[136:139], v181
	ds_read_b128 v[140:143], v181 offset:1024
	ds_read_b128 v[144:147], v181 offset:2048
	ds_read_b128 v[148:151], v181 offset:3072
	ds_read_b128 v[152:155], v182
	ds_read_b128 v[156:159], v182 offset:1024
	ds_read_b128 v[160:163], v182 offset:2048
	ds_read_b128 v[164:167], v182 offset:3072
	s_add_i32 s60, s44, 2
	s_add_u32 s45, s42, 0xfff80080
	s_addc_u32 s46, s43, -1
	s_cmp_eq_u32 s57, s44
	s_cselect_b32 s44, s39, s58
	s_cselect_b32 s47, s25, s46
	s_cselect_b32 s46, s29, s45
	s_cselect_b32 s45, s27, s59
	ds_read_b128 v[168:171], v183
	ds_read_b128 v[172:175], v183 offset:1024
	ds_read_b128 v[186:189], v183 offset:2048
	ds_read_b128 v[204:207], v183 offset:3072
	ds_read_b128 v[208:211], v183 offset:4096
	ds_read_b128 v[212:215], v183 offset:5120
	ds_read_b128 v[216:219], v183 offset:6144
	ds_read_b128 v[220:223], v183 offset:7168
	s_mov_b32 m0, s48
	s_nop 0
	global_load_lds_dwordx4 v128, s[100:101]
	s_mov_b32 m0, s49
	s_nop 0
	global_load_lds_dwordx4 v130, s[100:101]
	s_add_i32 m0, s13, 0xc000
	s_nop 0
	global_load_lds_dwordx4 v128, s[42:43]
	s_add_i32 m0, s13, 0xe000
	s_nop 0
	global_load_lds_dwordx4 v130, s[42:43]
	s_waitcnt vmcnt(8)
	s_waitcnt lgkmcnt(0)
	s_setprio 1
	s_barrier
	v_mfma_f32_16x16x32_bf16 v[124:127], v[136:139], v[168:171], v[124:127]
	v_mfma_f32_16x16x32_bf16 v[120:123], v[144:147], v[168:171], v[120:123]
	v_mfma_f32_16x16x32_bf16 v[108:111], v[136:139], v[186:189], v[108:111]
	v_mfma_f32_16x16x32_bf16 v[104:107], v[144:147], v[186:189], v[104:107]
	v_mfma_f32_16x16x32_bf16 v[92:95], v[136:139], v[208:211], v[92:95]
	v_mfma_f32_16x16x32_bf16 v[88:91], v[144:147], v[208:211], v[88:91]
	v_mfma_f32_16x16x32_bf16 v[76:79], v[136:139], v[216:219], v[76:79]
	v_mfma_f32_16x16x32_bf16 v[72:75], v[144:147], v[216:219], v[72:75]
	v_mfma_f32_16x16x32_bf16 v[124:127], v[140:143], v[172:175], v[124:127]
	v_mfma_f32_16x16x32_bf16 v[120:123], v[148:151], v[172:175], v[120:123]
	v_mfma_f32_16x16x32_bf16 v[108:111], v[140:143], v[204:207], v[108:111]
	v_mfma_f32_16x16x32_bf16 v[104:107], v[148:151], v[204:207], v[104:107]
	v_mfma_f32_16x16x32_bf16 v[92:95], v[140:143], v[212:215], v[92:95]
	v_mfma_f32_16x16x32_bf16 v[88:91], v[148:151], v[212:215], v[88:91]
	v_mfma_f32_16x16x32_bf16 v[76:79], v[140:143], v[220:223], v[76:79]
	v_mfma_f32_16x16x32_bf16 v[72:75], v[148:151], v[220:223], v[72:75]
	v_mfma_f32_16x16x32_bf16 v[116:119], v[152:155], v[168:171], v[116:119]
	v_mfma_f32_16x16x32_bf16 v[112:115], v[160:163], v[168:171], v[112:115]
	v_mfma_f32_16x16x32_bf16 v[100:103], v[152:155], v[186:189], v[100:103]
	v_mfma_f32_16x16x32_bf16 v[96:99], v[160:163], v[186:189], v[96:99]
	v_mfma_f32_16x16x32_bf16 v[84:87], v[152:155], v[208:211], v[84:87]
	v_mfma_f32_16x16x32_bf16 v[80:83], v[160:163], v[208:211], v[80:83]
	v_mfma_f32_16x16x32_bf16 v[68:71], v[152:155], v[216:219], v[68:71]
	v_mfma_f32_16x16x32_bf16 v[64:67], v[160:163], v[216:219], v[64:67]
	v_mfma_f32_16x16x32_bf16 v[116:119], v[156:159], v[172:175], v[116:119]
	v_mfma_f32_16x16x32_bf16 v[112:115], v[164:167], v[172:175], v[112:115]
	v_mfma_f32_16x16x32_bf16 v[100:103], v[156:159], v[204:207], v[100:103]
	v_mfma_f32_16x16x32_bf16 v[96:99], v[164:167], v[204:207], v[96:99]
	v_mfma_f32_16x16x32_bf16 v[84:87], v[156:159], v[212:215], v[84:87]
	v_mfma_f32_16x16x32_bf16 v[80:83], v[164:167], v[212:215], v[80:83]
	v_mfma_f32_16x16x32_bf16 v[68:71], v[156:159], v[220:223], v[68:71]
	v_mfma_f32_16x16x32_bf16 v[64:67], v[164:167], v[220:223], v[64:67]
	s_barrier
	s_add_u32 s98, s44, s20
	s_addc_u32 s99, s45, s21
	s_add_u32 s100, s46, s20
	s_addc_u32 s101, s47, s21
	s_setprio 0
	s_add_i32 s61, s51, s2
	s_mov_b32 m0, s61
	ds_read_b128 v[168:171], v183 offset:16384
	ds_read_b128 v[172:175], v183 offset:17408
	ds_read_b128 v[186:189], v183 offset:18432
	ds_read_b128 v[204:207], v183 offset:19456
	ds_read_b128 v[208:211], v183 offset:20480
	ds_read_b128 v[212:215], v183 offset:21504
	ds_read_b128 v[216:219], v183 offset:22528
	ds_read_b128 v[220:223], v183 offset:23552
	global_load_lds_dwordx4 v192, s[44:45]
	s_add_i32 m0, s61, 0x2000
	s_add_u32 s62, s44, 0x80000
	s_addc_u32 s63, s45, 0
	s_add_i32 s61, s52, s2
	global_load_lds_dwordx4 v196, s[44:45]
	s_mov_b32 m0, s61
	s_nop 0
	global_load_lds_dwordx4 v192, s[62:63]
	s_add_i32 m0, s61, 0x2000
	s_nop 0
	global_load_lds_dwordx4 v196, s[62:63]
	s_waitcnt vmcnt(6)
	s_waitcnt lgkmcnt(0)
	s_setprio 1
	s_barrier
	v_mfma_f32_16x16x32_bf16 v[60:63], v[136:139], v[168:171], v[60:63]
	v_mfma_f32_16x16x32_bf16 v[56:59], v[144:147], v[168:171], v[56:59]
	v_mfma_f32_16x16x32_bf16 v[44:47], v[136:139], v[186:189], v[44:47]
	v_mfma_f32_16x16x32_bf16 v[40:43], v[144:147], v[186:189], v[40:43]
	v_mfma_f32_16x16x32_bf16 v[28:31], v[136:139], v[208:211], v[28:31]
	v_mfma_f32_16x16x32_bf16 v[24:27], v[144:147], v[208:211], v[24:27]
	v_mfma_f32_16x16x32_bf16 v[12:15], v[136:139], v[216:219], v[12:15]
	v_mfma_f32_16x16x32_bf16 v[8:11], v[144:147], v[216:219], v[8:11]
	v_mfma_f32_16x16x32_bf16 v[60:63], v[140:143], v[172:175], v[60:63]
	v_mfma_f32_16x16x32_bf16 v[56:59], v[148:151], v[172:175], v[56:59]
	v_mfma_f32_16x16x32_bf16 v[44:47], v[140:143], v[204:207], v[44:47]
	v_mfma_f32_16x16x32_bf16 v[40:43], v[148:151], v[204:207], v[40:43]
	v_mfma_f32_16x16x32_bf16 v[28:31], v[140:143], v[212:215], v[28:31]
	v_mfma_f32_16x16x32_bf16 v[24:27], v[148:151], v[212:215], v[24:27]
	v_mfma_f32_16x16x32_bf16 v[12:15], v[140:143], v[220:223], v[12:15]
	v_mfma_f32_16x16x32_bf16 v[8:11], v[148:151], v[220:223], v[8:11]
	v_mfma_f32_16x16x32_bf16 v[52:55], v[152:155], v[168:171], v[52:55]
	v_mfma_f32_16x16x32_bf16 v[48:51], v[160:163], v[168:171], v[48:51]
	v_mfma_f32_16x16x32_bf16 v[36:39], v[152:155], v[186:189], v[36:39]
	v_mfma_f32_16x16x32_bf16 v[32:35], v[160:163], v[186:189], v[32:35]
	v_mfma_f32_16x16x32_bf16 v[20:23], v[152:155], v[208:211], v[20:23]
	v_mfma_f32_16x16x32_bf16 v[16:19], v[160:163], v[208:211], v[16:19]
	v_mfma_f32_16x16x32_bf16 v[4:7], v[152:155], v[216:219], v[4:7]
	v_mfma_f32_16x16x32_bf16 v[0:3], v[160:163], v[216:219], v[0:3]
	v_mfma_f32_16x16x32_bf16 v[52:55], v[156:159], v[172:175], v[52:55]
	v_mfma_f32_16x16x32_bf16 v[48:51], v[164:167], v[172:175], v[48:51]
	v_mfma_f32_16x16x32_bf16 v[36:39], v[156:159], v[204:207], v[36:39]
	v_mfma_f32_16x16x32_bf16 v[32:35], v[164:167], v[204:207], v[32:35]
	v_mfma_f32_16x16x32_bf16 v[20:23], v[156:159], v[212:215], v[20:23]
	v_mfma_f32_16x16x32_bf16 v[16:19], v[164:167], v[212:215], v[16:19]
	v_mfma_f32_16x16x32_bf16 v[4:7], v[156:159], v[220:223], v[4:7]
	v_mfma_f32_16x16x32_bf16 v[0:3], v[164:167], v[220:223], v[0:3]
	s_barrier
; #define PG8_STAGE(bufoff, gbase, voff) do { _Pragma("unroll") for (int _i = 0; _i < 2; ++_i) \
;         __builtin_amdgcn_global_load_lds((const unsigned*)((const char*)(gbase) + (voff)[_i]), (PG8_LAS unsigned*)(lds + (bufoff) + ldsw + _i * 8192), 16, 0, 0); } while (0)
; #define PG8_LDA(dst, b, h) do { _Pragma("unroll") for (int m = 0; m < 4; ++m) _Pragma("unroll") for (int k = 0; k < 2; ++k) dst[m][k] = *(const PG8_LAS bf16x8*)(lds + PG8_SA(b, h) + aoff + m * 2048 + k * 1024); } while (0)
; #define PG8_LDB(dst, b, h) do { _Pragma("unroll") for (int n = 0; n < 2; ++n) _Pragma("unroll") for (int k = 0; k < 2; ++k) dst[n][k] = *(const PG8_LAS bf16x8*)(lds + PG8_SB(b, h) + boff + n * 2048 + k * 1024); } while (0)
; #define PG8_MMA(ai, bj, At, Bt) do { __builtin_amdgcn_s_setprio(1); _Pragma("unroll") for (int m = 0; m < 4; ++m) _Pragma("unroll") for (int n = 0; n < 2; ++n) _Pragma("unroll") for (int k = 0; k < 2; ++k) \
;         acc[ai][bj][m][n] = __builtin_amdgcn_mfma_f32_16x16x32_bf16(Bt[n][k], At[m][k], acc[ai][bj][m][n], 0, 0, 0); __builtin_amdgcn_s_setprio(0); } while (0)
; #define PG8_WAIT_V(n) asm volatile("s_waitcnt vmcnt(" #n ")" ::: "memory")
; #define PG8_WAIT_L(n) asm volatile("s_waitcnt lgkmcnt(" #n ")" ::: "memory")
; #define PG8_BAR __builtin_amdgcn_s_barrier()
; #define PG8_SCHED __builtin_amdgcn_sched_barrier(0)
; template <class Epi, class Sched, bool ALIGN_EPI = false, bool SP2 = false>
; __device__ __forceinline__ void gemm_phase(PG8_LAS unsigned char* lds, const Gemm g, const Sched& S, const Epi& E) {
;     ...
;             PG8_LDB(B0, 1, 0); PG8_LDB(B1, 1, 1); PG8_SCHED; PG8_LDA(At, 1, 0); PG8_STAGE(PG8_SA(0, 1), a2 + hstepA, voffA);
;             PG8_WAIT_V(8); PG8_WAIT_L(0); PG8_BAR; PG8_MMA(0, 0, At, B0); PG8_MMA(0, 1, At, B1); PG8_BAR; PG8_SCHED;
;             PG8_LDA(At, 1, 1); PG8_STAGE(PG8_SB(1, 0), b3, voffB); PG8_STAGE(PG8_SB(1, 1), b3 + hstepB, voffB); PG8_STAGE(PG8_SA(1, 0), a3, voffA);
;             PG8_WAIT_V(8); PG8_WAIT_L(0); PG8_BAR; PG8_MMA(1, 0, At, B0); PG8_MMA(1, 1, At, B1); PG8_BAR; PG8_SCHED;
	s_setprio 0
	s_add_i32 s61, 0, 0x18000
	s_add_i32 s62, 0, 0x1c000
	v_add_u32_e32 v148, s61, v179
	v_add_u32_e32 v164, s62, v179
	ds_read_b128 v[136:139], v148
	ds_read_b128 v[140:143], v148 offset:1024
	ds_read_b128 v[144:147], v148 offset:2048
	ds_read_b128 v[148:151], v148 offset:3072
	ds_read_b128 v[152:155], v164
	ds_read_b128 v[156:159], v164 offset:1024
	ds_read_b128 v[160:163], v164 offset:2048
	ds_read_b128 v[164:167], v164 offset:3072
	s_mov_b32 m0, s13
	s_nop 0
	global_load_lds_dwordx4 v192, s[46:47]
	s_mov_b32 m0, s14
	s_nop 0
	global_load_lds_dwordx4 v196, s[46:47]
	s_add_u32 s46, s46, 0x80000
	s_addc_u32 s47, s47, 0
	s_mov_b32 m0, s15
	ds_read_b128 v[168:171], v183 offset:32768
	ds_read_b128 v[172:175], v183 offset:33792
	ds_read_b128 v[186:189], v183 offset:34816
	ds_read_b128 v[204:207], v183 offset:35840
	ds_read_b128 v[208:211], v183 offset:36864
	ds_read_b128 v[212:215], v183 offset:37888
	ds_read_b128 v[216:219], v183 offset:38912
	ds_read_b128 v[220:223], v183 offset:39936
	global_load_lds_dwordx4 v192, s[46:47]
	s_mov_b32 m0, s41
	s_nop 0
	global_load_lds_dwordx4 v196, s[46:47]
	s_waitcnt vmcnt(8)
	s_waitcnt lgkmcnt(0)
	s_setprio 1
	s_barrier
	v_mfma_f32_16x16x32_bf16 v[124:127], v[136:139], v[168:171], v[124:127]
	v_mfma_f32_16x16x32_bf16 v[120:123], v[144:147], v[168:171], v[120:123]
	v_mfma_f32_16x16x32_bf16 v[108:111], v[136:139], v[186:189], v[108:111]
	v_mfma_f32_16x16x32_bf16 v[104:107], v[144:147], v[186:189], v[104:107]
	v_mfma_f32_16x16x32_bf16 v[92:95], v[136:139], v[208:211], v[92:95]
	v_mfma_f32_16x16x32_bf16 v[88:91], v[144:147], v[208:211], v[88:91]
	v_mfma_f32_16x16x32_bf16 v[76:79], v[136:139], v[216:219], v[76:79]
	v_mfma_f32_16x16x32_bf16 v[72:75], v[144:147], v[216:219], v[72:75]
	v_mfma_f32_16x16x32_bf16 v[124:127], v[140:143], v[172:175], v[124:127]
	v_mfma_f32_16x16x32_bf16 v[120:123], v[148:151], v[172:175], v[120:123]
	v_mfma_f32_16x16x32_bf16 v[108:111], v[140:143], v[204:207], v[108:111]
	v_mfma_f32_16x16x32_bf16 v[104:107], v[148:151], v[204:207], v[104:107]
	v_mfma_f32_16x16x32_bf16 v[92:95], v[140:143], v[212:215], v[92:95]
	v_mfma_f32_16x16x32_bf16 v[88:91], v[148:151], v[212:215], v[88:91]
	v_mfma_f32_16x16x32_bf16 v[76:79], v[140:143], v[220:223], v[76:79]
	v_mfma_f32_16x16x32_bf16 v[72:75], v[148:151], v[220:223], v[72:75]
	v_mfma_f32_16x16x32_bf16 v[116:119], v[152:155], v[168:171], v[116:119]
	v_mfma_f32_16x16x32_bf16 v[112:115], v[160:163], v[168:171], v[112:115]
	v_mfma_f32_16x16x32_bf16 v[100:103], v[152:155], v[186:189], v[100:103]
	v_mfma_f32_16x16x32_bf16 v[96:99], v[160:163], v[186:189], v[96:99]
	v_mfma_f32_16x16x32_bf16 v[84:87], v[152:155], v[208:211], v[84:87]
	v_mfma_f32_16x16x32_bf16 v[80:83], v[160:163], v[208:211], v[80:83]
	v_mfma_f32_16x16x32_bf16 v[68:71], v[152:155], v[216:219], v[68:71]
	v_mfma_f32_16x16x32_bf16 v[64:67], v[160:163], v[216:219], v[64:67]
	v_mfma_f32_16x16x32_bf16 v[116:119], v[156:159], v[172:175], v[116:119]
	v_mfma_f32_16x16x32_bf16 v[112:115], v[164:167], v[172:175], v[112:115]
	v_mfma_f32_16x16x32_bf16 v[100:103], v[156:159], v[204:207], v[100:103]
	v_mfma_f32_16x16x32_bf16 v[96:99], v[164:167], v[204:207], v[96:99]
	v_mfma_f32_16x16x32_bf16 v[84:87], v[156:159], v[212:215], v[84:87]
	v_mfma_f32_16x16x32_bf16 v[80:83], v[164:167], v[212:215], v[80:83]
	v_mfma_f32_16x16x32_bf16 v[68:71], v[156:159], v[220:223], v[68:71]
	v_mfma_f32_16x16x32_bf16 v[64:67], v[164:167], v[220:223], v[64:67]
	s_barrier
	s_setprio 0
	s_add_i32 s46, s61, s2
	s_mov_b32 m0, s46
	ds_read_b128 v[168:171], v183 offset:49152
	ds_read_b128 v[172:175], v183 offset:50176
	ds_read_b128 v[186:189], v183 offset:51200
	ds_read_b128 v[204:207], v183 offset:52224
	ds_read_b128 v[208:211], v183 offset:53248
	ds_read_b128 v[212:215], v183 offset:54272
	ds_read_b128 v[216:219], v183 offset:55296
	ds_read_b128 v[220:223], v183 offset:56320
	global_load_lds_dwordx4 v192, s[98:99]
	s_add_i32 m0, s46, 0x2000
	s_add_u32 s44, s44, 0x80080
	s_addc_u32 s45, s45, 0
	s_add_i32 s46, s62, s2
	global_load_lds_dwordx4 v196, s[98:99]
	s_mov_b32 m0, s46
	s_nop 0
	global_load_lds_dwordx4 v192, s[44:45]
	s_add_i32 m0, s46, 0x2000
	s_nop 0
	global_load_lds_dwordx4 v196, s[44:45]
	s_waitcnt vmcnt(6)
	s_waitcnt lgkmcnt(0)
	s_setprio 1
	s_barrier
	v_mfma_f32_16x16x32_bf16 v[60:63], v[136:139], v[168:171], v[60:63]
	v_mfma_f32_16x16x32_bf16 v[56:59], v[144:147], v[168:171], v[56:59]
	v_mfma_f32_16x16x32_bf16 v[44:47], v[136:139], v[186:189], v[44:47]
	v_mfma_f32_16x16x32_bf16 v[40:43], v[144:147], v[186:189], v[40:43]
	v_mfma_f32_16x16x32_bf16 v[28:31], v[136:139], v[208:211], v[28:31]
	v_mfma_f32_16x16x32_bf16 v[24:27], v[144:147], v[208:211], v[24:27]
	v_mfma_f32_16x16x32_bf16 v[12:15], v[136:139], v[216:219], v[12:15]
	v_mfma_f32_16x16x32_bf16 v[8:11], v[144:147], v[216:219], v[8:11]
	v_mfma_f32_16x16x32_bf16 v[60:63], v[140:143], v[172:175], v[60:63]
	v_mfma_f32_16x16x32_bf16 v[56:59], v[148:151], v[172:175], v[56:59]
	v_mfma_f32_16x16x32_bf16 v[44:47], v[140:143], v[204:207], v[44:47]
	v_mfma_f32_16x16x32_bf16 v[40:43], v[148:151], v[204:207], v[40:43]
	v_mfma_f32_16x16x32_bf16 v[28:31], v[140:143], v[212:215], v[28:31]
	v_mfma_f32_16x16x32_bf16 v[24:27], v[148:151], v[212:215], v[24:27]
	v_mfma_f32_16x16x32_bf16 v[12:15], v[140:143], v[220:223], v[12:15]
	v_mfma_f32_16x16x32_bf16 v[8:11], v[148:151], v[220:223], v[8:11]
	v_mfma_f32_16x16x32_bf16 v[52:55], v[152:155], v[168:171], v[52:55]
	v_mfma_f32_16x16x32_bf16 v[48:51], v[160:163], v[168:171], v[48:51]
	v_mfma_f32_16x16x32_bf16 v[36:39], v[152:155], v[186:189], v[36:39]
	v_mfma_f32_16x16x32_bf16 v[32:35], v[160:163], v[186:189], v[32:35]
	v_mfma_f32_16x16x32_bf16 v[20:23], v[152:155], v[208:211], v[20:23]
	v_mfma_f32_16x16x32_bf16 v[16:19], v[160:163], v[208:211], v[16:19]
	v_mfma_f32_16x16x32_bf16 v[4:7], v[152:155], v[216:219], v[4:7]
	v_mfma_f32_16x16x32_bf16 v[0:3], v[160:163], v[216:219], v[0:3]
	v_mfma_f32_16x16x32_bf16 v[52:55], v[156:159], v[172:175], v[52:55]
	v_mfma_f32_16x16x32_bf16 v[48:51], v[164:167], v[172:175], v[48:51]
	v_mfma_f32_16x16x32_bf16 v[36:39], v[156:159], v[204:207], v[36:39]
	v_mfma_f32_16x16x32_bf16 v[32:35], v[164:167], v[204:207], v[32:35]
	v_mfma_f32_16x16x32_bf16 v[20:23], v[156:159], v[212:215], v[20:23]
	v_mfma_f32_16x16x32_bf16 v[16:19], v[164:167], v[212:215], v[16:19]
	v_mfma_f32_16x16x32_bf16 v[4:7], v[156:159], v[220:223], v[4:7]
	v_mfma_f32_16x16x32_bf16 v[0:3], v[164:167], v[220:223], v[0:3]
	s_barrier
	s_setprio 0
	s_add_u32 s42, s42, 0x100
	s_addc_u32 s43, s43, 0
	s_add_u32 s58, s58, 0x100
	s_addc_u32 s59, s59, 0
	s_cmp_eq_u32 s32, 0
	s_cbranch_scc1 .Lml8_skip
	s_cmp_eq_u32 s60, 18
	s_cbranch_scc0 .Lml8_a
	s_add_u32 s100, s90, 0x3800
	s_addc_u32 s101, s91, 0
	v_mov_b32_e32 v227, 0
	global_load_dword v226, v227, s[100:101] sc1
	s_branch .Lml8_skip
; #define PG8_BAR __builtin_amdgcn_s_barrier()
; template <class Epi, class Sched, bool ALIGN_EPI = false, bool SP2 = false>
; __device__ __forceinline__ void gemm_phase(PG8_LAS unsigned char* lds, const Gemm g, const Sched& S, const Epi& E) {
;     ...
;         for (int t = 0; t < nt; t += 2) {
;             const bool last = (t == nt - 2);
;             const char* a1 = cA + (size_t)(t + 1) * kstepA;
;             const char* a2 = last ? nA : cA + (size_t)(t + 2) * kstepA; const char* b2 = last ? nB : cB + (size_t)(t + 2) * kstepB;
;             const char* a3 = a2 + kstepA; const char* b3 = b2 + kstepB;
;             if (last && has_next) S.a_ready(nxt);
;     ...
;         if constexpr (ALIGN_EPI) { if (wr == 0) PG8_BAR; }
;         if constexpr (!Epi::AFTER_DRAIN) { if (cur.part < 0) E(acc, cur, wr, wc, fr, fq); else store_part<Epi::PERM>(acc, cur, g.part, wr, wc, fr, fq); S.done(cur); }
.Lml8_a:
	s_cmp_eq_u32 s60, 24
	s_cbranch_scc0 .Lml8_skip
	s_waitcnt vmcnt(0)
	v_readfirstlane_b32 s98, v226
	s_cmpk_lt_u32 s98, 0x80
	s_cbranch_scc0 .Lml8_got
	s_add_u32 s100, s90, 0x3800
	s_addc_u32 s101, s91, 0
.Lml8_spin:
	global_load_dword v226, v227, s[100:101] sc1
	s_waitcnt vmcnt(0)
	v_readfirstlane_b32 s98, v226
	s_cmpk_lt_u32 s98, 0x80
	s_cbranch_scc0 .Lml8_got
	s_sleep 2
	s_branch .Lml8_spin
.Lml8_got:
	buffer_inv sc1
	s_mov_b32 s32, 0
.Lml8_skip:
	s_cmp_ge_i32 s60, s56
	s_mov_b32 s44, s60
	s_cbranch_scc0 .LBB0_1113
	s_and_b64 vcc, exec, s[22:23]
	s_cbranch_vccnz .LBB0_1118
	s_mov_b64 s[42:43], -1
	s_cmp_gt_i32 s16, -1
	v_lshl_or_b32 v136, s40, 8, v180
	s_cbranch_scc1 .LBB0_1119
